# DA softmax block: bf16 conversions interleaved between the exps (two pairs behind) instead of after them
# speedup vs baseline: 1.0063x; 1.0027x over previous
.LBB0_610:
	v_exp_f32_e32 v98, v98
	v_exp_f32_e32 v99, v99
	v_exp_f32_e32 v100, v100
	v_exp_f32_e32 v101, v101
	v_exp_f32_e32 v102, v102
	v_exp_f32_e32 v103, v103
	v_cvt_pk_bf16_f32 v142, v98, v99
	v_exp_f32_e32 v104, v104
	v_exp_f32_e32 v105, v105
	v_cvt_pk_bf16_f32 v143, v100, v101
	v_exp_f32_e32 v106, v106
	v_exp_f32_e32 v107, v107
	v_cvt_pk_bf16_f32 v144, v102, v103
	v_exp_f32_e32 v108, v108
	v_exp_f32_e32 v109, v109
	v_cvt_pk_bf16_f32 v145, v104, v105
	v_exp_f32_e32 v110, v110
	v_exp_f32_e32 v111, v111
	v_cvt_pk_bf16_f32 v138, v106, v107
	v_exp_f32_e32 v112, v112
	v_exp_f32_e32 v113, v113
	v_cvt_pk_bf16_f32 v139, v108, v109
	v_exp_f32_e32 v82, v82
	v_exp_f32_e32 v83, v83
	v_cvt_pk_bf16_f32 v140, v110, v111
	v_exp_f32_e32 v84, v84
	v_exp_f32_e32 v85, v85
	v_cvt_pk_bf16_f32 v141, v112, v113
	v_exp_f32_e32 v86, v86
	v_exp_f32_e32 v87, v87
	v_cvt_pk_bf16_f32 v134, v82, v83
	v_exp_f32_e32 v88, v88
	v_exp_f32_e32 v89, v89
	v_cvt_pk_bf16_f32 v135, v84, v85
	v_exp_f32_e32 v90, v90
	v_exp_f32_e32 v91, v91
	v_cvt_pk_bf16_f32 v136, v86, v87
	v_exp_f32_e32 v92, v92
	v_exp_f32_e32 v93, v93
	v_cvt_pk_bf16_f32 v137, v88, v89
	v_exp_f32_e32 v94, v94
	v_exp_f32_e32 v95, v95
	v_cvt_pk_bf16_f32 v130, v90, v91
	v_exp_f32_e32 v96, v96
	v_exp_f32_e32 v97, v97
	v_cvt_pk_bf16_f32 v131, v92, v93
	v_cvt_pk_bf16_f32 v132, v94, v95
	v_cvt_pk_bf16_f32 v133, v96, v97
	s_and_b64 vcc, exec, s[2:3]
	s_cbranch_vccnz .LBB0_612
	s_waitcnt vmcnt(1)
